# prenorm/prenorm_bf loops: all shift-scale loads hoisted to iteration top so next-row prefetch stays in flight; own epilogue gate loads issued up front
# speedup vs baseline: 1.0153x; 1.0025x over previous
.LBB0_69:
	s_waitcnt vmcnt(4)
	v_mov_b32_e32 v56, v29
	v_mov_b32_e32 v57, v25
	v_ashrrev_i32_e32 v43, 12, v41
	v_mov_b32_e32 v54, v9
	v_mov_b32_e32 v55, v1
	v_pk_mul_f32 v[72:73], v[56:57], v[56:57]
	v_mul_i32_i24_e32 v56, 0xc00, v43
	v_mov_b32_e32 v52, v8
	v_mov_b32_e32 v53, v0
	v_pk_mul_f32 v[54:55], v[54:55], v[54:55]
	v_ashrrev_i32_e32 v57, 31, v56
	v_pk_fma_f32 v[74:75], v[52:53], v[52:53], v[54:55]
	v_lshl_add_u64 v[52:53], v[56:57], 2, s[38:39]
	v_lshl_add_u64 v[76:77], v[52:53], 0, s[8:9]
	v_lshl_add_u64 v[78:79], v[52:53], 0, v[32:33]
	v_lshl_add_u64 v[56:57], v[76:77], 0, v[32:33]
	global_load_dwordx4 v[52:55], v[78:79], off
	s_nop 0
	global_load_dwordx4 v[84:87], v[56:57], off
	global_load_dwordx4 v[88:91], v[56:57], off offset:1024
	global_load_dwordx4 v[92:95], v[78:79], off offset:1024
	global_load_dwordx4 v[96:99], v[56:57], off offset:2048
	global_load_dwordx4 v[100:103], v[78:79], off offset:2048
	global_load_dwordx4 v[104:107], v[56:57], off offset:3072
	global_load_dwordx4 v[108:111], v[78:79], off offset:3072
	v_mov_b32_e32 v68, v28
	v_mov_b32_e32 v69, v24
	v_mov_b32_e32 v64, v30
	v_mov_b32_e32 v65, v26
	v_pk_fma_f32 v[68:69], v[68:69], v[68:69], v[72:73]
	v_mov_b32_e32 v60, v10
	v_mov_b32_e32 v61, v2
	v_add_u32_e32 v51, s88, v41
	v_mov_b32_e32 v66, v31
	v_mov_b32_e32 v67, v27
	v_pk_fma_f32 v[64:65], v[64:65], v[64:65], v[68:69]
	v_mov_b32_e32 v62, v11
	v_mov_b32_e32 v63, v3
	v_cmp_gt_i32_e32 vcc, s10, v51
	v_pk_fma_f32 v[60:61], v[60:61], v[60:61], v[74:75]
	v_pk_fma_f32 v[82:83], v[66:67], v[66:67], v[64:65]
	v_mov_b32_e32 v39, v33
	v_cndmask_b32_e32 v70, v41, v51, vcc
	v_pk_fma_f32 v[80:81], v[62:63], v[62:63], v[60:61]
	v_add_f32_e32 v41, v82, v83
	v_lshl_add_u64 v[82:83], v[76:77], 0, v[38:39]
	v_add_f32_e32 v39, v41, v80
	v_add_f32_e32 v39, v39, v81
	ds_bpermute_b32 v41, v44, v39
	v_ashrrev_i32_e32 v71, 31, v70
	v_lshlrev_b64 v[70:71], 12, v[70:71]
	v_lshl_add_u64 v[72:73], v[34:35], 0, v[70:71]
	global_load_dwordx4 v[60:63], v[72:73], off nt
	global_load_dwordx4 v[64:67], v[72:73], off offset:1024 nt
	global_load_dwordx4 v[68:71], v[72:73], off offset:2048 nt
	s_nop 0
	global_load_dwordx4 v[72:75], v[72:73], off offset:3072 nt
	s_waitcnt lgkmcnt(0)
	v_add_f32_e32 v39, v39, v41
	ds_bpermute_b32 v41, v45, v39
	v_mov_b32_e32 v43, v33
	s_waitcnt lgkmcnt(0)
	v_add_f32_e32 v39, v39, v41
	ds_bpermute_b32 v41, v46, v39
	s_waitcnt lgkmcnt(0)
	v_add_f32_e32 v39, v39, v41
	ds_bpermute_b32 v41, v47, v39
	s_waitcnt lgkmcnt(0)
	v_add_f32_e32 v39, v39, v41
	ds_bpermute_b32 v41, v48, v39
	s_waitcnt lgkmcnt(0)
	v_add_f32_e32 v39, v39, v41
	ds_bpermute_b32 v41, v49, v39
	s_waitcnt lgkmcnt(0)
	v_add_f32_e32 v39, v39, v41
	v_fmamk_f32 v39, v39, 0x3a800000, v50
	v_mul_f32_e32 v41, 0x4b800000, v39
	v_cmp_gt_f32_e32 vcc, s12, v39
	s_waitcnt vmcnt(4)
	v_pk_add_f32 v[56:57], v[84:85], 1.0 op_sel_hi:[1,0]
	v_cndmask_b32_e32 v39, v39, v41, vcc
	v_rsq_f32_e32 v39, v39
	v_pk_add_f32 v[58:59], v[86:87], 1.0 op_sel_hi:[1,0]
	v_mul_f32_e32 v41, 0x45800000, v39
	v_cndmask_b32_e32 v80, v39, v41, vcc
	v_pk_mul_f32 v[28:29], v[28:29], v[80:81] op_sel_hi:[1,0]
	v_pk_mul_f32 v[30:31], v[30:31], v[80:81] op_sel_hi:[1,0]
	v_pk_mul_f32 v[28:29], v[4:5], v[28:29]
	v_pk_mul_f32 v[30:31], v[6:7], v[30:31]
	v_pk_fma_f32 v[28:29], v[56:57], v[28:29], v[52:53]
	v_pk_fma_f32 v[30:31], v[58:59], v[30:31], v[54:55]
	v_cvt_pk_bf16_f32 v28, v28, v29
	v_cvt_pk_bf16_f32 v29, v30, v31
	global_store_dwordx2 v[36:37], v[28:29], off
	v_pk_mul_f32 v[24:25], v[24:25], v[80:81] op_sel_hi:[1,0]
	v_pk_mul_f32 v[26:27], v[26:27], v[80:81] op_sel_hi:[1,0]
	v_pk_mul_f32 v[24:25], v[12:13], v[24:25]
	v_pk_mul_f32 v[26:27], v[14:15], v[26:27]
	v_mov_b32_e32 v41, v33
	v_lshl_add_u64 v[56:57], v[76:77], 0, v[40:41]
	v_pk_mul_f32 v[8:9], v[8:9], v[80:81] op_sel_hi:[1,0]
	v_pk_mul_f32 v[10:11], v[10:11], v[80:81] op_sel_hi:[1,0]
	v_pk_mul_f32 v[8:9], v[16:17], v[8:9]
	v_pk_mul_f32 v[10:11], v[18:19], v[10:11]
	v_pk_mul_f32 v[0:1], v[0:1], v[80:81] op_sel_hi:[1,0]
	v_pk_mul_f32 v[2:3], v[2:3], v[80:81] op_sel_hi:[1,0]
	v_cmp_lt_i32_e32 vcc, s11, v51
	v_mov_b32_e32 v41, v51
	s_or_b64 s[6:7], vcc, s[6:7]
	v_pk_add_f32 v[28:29], v[88:89], 1.0 op_sel_hi:[1,0]
	v_pk_add_f32 v[30:31], v[90:91], 1.0 op_sel_hi:[1,0]
	v_pk_fma_f32 v[24:25], v[24:25], v[28:29], v[92:93]
	v_pk_fma_f32 v[26:27], v[26:27], v[30:31], v[94:95]
	v_cvt_pk_bf16_f32 v24, v24, v25
	v_cvt_pk_bf16_f32 v25, v26, v27
	global_store_dwordx2 v[36:37], v[24:25], off offset:512
	v_lshl_add_u64 v[52:53], v[76:77], 0, v[42:43]
	v_pk_mul_f32 v[76:77], v[20:21], v[0:1]
	v_pk_add_f32 v[24:25], v[96:97], 1.0 op_sel_hi:[1,0]
	v_pk_add_f32 v[26:27], v[98:99], 1.0 op_sel_hi:[1,0]
	v_pk_fma_f32 v[8:9], v[8:9], v[24:25], v[100:101]
	v_pk_fma_f32 v[10:11], v[10:11], v[26:27], v[102:103]
	v_cvt_pk_bf16_f32 v8, v8, v9
	v_cvt_pk_bf16_f32 v9, v10, v11
	global_store_dwordx2 v[36:37], v[8:9], off offset:1024
	v_pk_mul_f32 v[78:79], v[22:23], v[2:3]
	v_pk_add_f32 v[52:53], v[104:105], 1.0 op_sel_hi:[1,0]
	v_pk_add_f32 v[54:55], v[106:107], 1.0 op_sel_hi:[1,0]
	v_pk_fma_f32 v[52:53], v[76:77], v[52:53], v[108:109]
	v_pk_fma_f32 v[54:55], v[78:79], v[54:55], v[110:111]
	v_cvt_pk_bf16_f32 v52, v52, v53
	v_cvt_pk_bf16_f32 v53, v54, v55
	global_store_dwordx2 v[36:37], v[52:53], off offset:1536
	v_lshl_add_u64 v[36:37], v[36:37], 0, s[4:5]
	s_waitcnt vmcnt(4)
	v_mov_b32_e32 v0, v72
	v_mov_b32_e32 v1, v73
	v_mov_b32_e32 v30, v62
	v_mov_b32_e32 v31, v63
	v_mov_b32_e32 v28, v60
	v_mov_b32_e32 v29, v61
	v_mov_b32_e32 v26, v66
	v_mov_b32_e32 v27, v67
	v_mov_b32_e32 v24, v64
	v_mov_b32_e32 v25, v65
	v_mov_b32_e32 v10, v70
	v_mov_b32_e32 v11, v71
	v_mov_b32_e32 v8, v68
	v_mov_b32_e32 v9, v69
	v_mov_b32_e32 v2, v74
	v_mov_b32_e32 v3, v75
	s_andn2_b64 exec, exec, s[6:7]
	s_cbranch_execnz .LBB0_69

.LBB0_277:
	s_ashr_i32 s0, s23, 7
	s_ashr_i32 s1, s0, 31
	s_lshl_b64 s[0:1], s[0:1], 22
	s_waitcnt vmcnt(3)
	v_lshlrev_b32_e32 v20, 10, v140
	v_mov_b32_e32 v21, v121
	v_lshl_add_u64 v[20:21], s[0:1], 0, v[20:21]
	v_lshlrev_b64 v[20:21], 1, v[20:21]
	s_lshl_b32 s0, s14, 7
	v_lshl_add_u64 v[22:23], s[70:71], 0, v[20:21]
	s_and_b32 s12, s0, 0x380
	v_lshl_add_u64 v[22:23], v[22:23], 0, s[12:13]
	v_mov_b32_e32 v75, v121
	v_lshl_add_u64 v[140:141], v[22:23], 0, v[74:75]
	s_mov_b64 s[72:73], 0x8000
	global_load_dwordx2 v[234:235], v[140:141], off offset:1024
	global_load_dwordx2 v[236:237], v[140:141], off offset:1056
	global_load_dwordx2 v[238:239], v[140:141], off offset:1088
	global_load_dwordx2 v[240:241], v[140:141], off offset:1120
	v_lshl_add_u64 v[250:251], v[140:141], 0, s[72:73]
	global_load_dwordx2 v[242:243], v[250:251], off offset:1024
	global_load_dwordx2 v[244:245], v[250:251], off offset:1056
	global_load_dwordx2 v[246:247], v[250:251], off offset:1088
	global_load_dwordx2 v[248:249], v[250:251], off offset:1120
	v_max_f32_e32 v22, v132, v132
	v_max_f32_e32 v23, v71, v71
	s_waitcnt vmcnt(9)
	v_max_f32_e32 v30, v23, v22
	v_sub_f32_e32 v22, v71, v30
	v_sub_f32_e32 v23, v132, v30
	v_exp_f32_e32 v22, v22
	v_exp_f32_e32 v23, v23
	v_max_f32_e32 v24, v148, v148
	v_max_f32_e32 v24, v30, v24
	v_mov_b32_e32 v132, v114
	v_sub_f32_e32 v30, v30, v24
	v_exp_f32_e32 v139, v30
	v_pk_mul_f32 v[30:31], v[132:133], v[22:23]
	v_sub_f32_e32 v65, v148, v24
	v_pk_fma_f32 v[132:133], v[132:133], v[22:23], v[30:31] op_sel_hi:[1,1,0]
	v_lshlrev_b32_e32 v26, 16, v142
	v_exp_f32_e32 v132, v65
	v_and_b32_e32 v27, 0xffff0000, v142
	v_lshlrev_b32_e32 v28, 16, v143
	v_and_b32_e32 v29, 0xffff0000, v143
	v_max_f32_e32 v25, v152, v152
	s_waitcnt vmcnt(8)
	v_pk_mul_f32 v[32:33], v[30:31], v[26:27] op_sel:[1,0]
	v_max_f32_e32 v25, v24, v25
	v_mov_b32_e32 v26, v139
	v_pk_mul_f32 v[148:149], v[30:31], v[28:29] op_sel:[1,0]
	v_pk_fma_f32 v[32:33], v[44:45], v[22:23], v[32:33] op_sel_hi:[1,0,1]
	v_sub_f32_e32 v24, v24, v25
	v_pk_fma_f32 v[44:45], v[46:47], v[22:23], v[148:149] op_sel_hi:[1,0,1]
	v_pk_mul_f32 v[46:47], v[26:27], v[32:33] op_sel_hi:[0,1]
	v_pk_mul_f32 v[32:33], v[138:139], v[132:133]
	v_sub_f32_e32 v67, v152, v25
	v_exp_f32_e32 v137, v24
	v_pk_fma_f32 v[132:133], v[138:139], v[132:133], v[32:33] op_sel_hi:[1,1,0]
	v_lshlrev_b32_e32 v34, 16, v150
	v_exp_f32_e32 v132, v67
	v_and_b32_e32 v35, 0xffff0000, v150
	v_mov_b32_e32 v28, v137
	v_pk_fma_f32 v[34:35], v[32:33], v[34:35], v[46:47] op_sel_hi:[0,1,1]
	v_pk_mul_f32 v[138:139], v[28:29], v[34:35] op_sel_hi:[0,1]
	v_pk_mul_f32 v[34:35], v[136:137], v[132:133]
	v_lshlrev_b32_e32 v142, 16, v151
	v_and_b32_e32 v143, 0xffff0000, v151
	v_pk_mul_f32 v[44:45], v[26:27], v[44:45] op_sel_hi:[0,1]
	v_add_f32_e32 v23, v34, v35
	v_pk_fma_f32 v[46:47], v[32:33], v[142:143], v[44:45] op_sel_hi:[0,1,1]
	v_rcp_f32_e32 v44, v23
	v_lshlrev_b32_e32 v150, 16, v154
	v_and_b32_e32 v151, 0xffff0000, v154
	v_lshlrev_b32_e32 v154, 16, v155
	v_and_b32_e32 v155, 0xffff0000, v155
	v_pk_mul_f32 v[46:47], v[28:29], v[46:47] op_sel_hi:[0,1]
	v_pk_fma_f32 v[132:133], v[34:35], v[150:151], v[138:139] op_sel_hi:[0,1,1]
	v_pk_fma_f32 v[46:47], v[34:35], v[154:155], v[46:47] op_sel_hi:[0,1,1]
	v_pk_mul_f32 v[132:133], v[44:45], v[132:133] op_sel_hi:[0,1]
	v_pk_mul_f32 v[46:47], v[44:45], v[46:47] op_sel_hi:[0,1]
	v_readlane_b32 s16, v254, 2
	v_readlane_b32 s17, v254, 3
	s_add_i32 s23, s23, s3
	s_cmpk_lt_i32 s23, 0x800
	v_lshl_add_u64 v[24:25], s[16:17], 0, v[20:21]
	v_lshl_add_u64 v[24:25], v[24:25], 0, s[12:13]
	v_lshl_add_u64 v[24:25], v[24:25], 0, v[74:75]
	v_or_b32_e32 v20, 0x8000, v20
	v_readlane_b32 s18, v254, 4
	v_readlane_b32 s19, v254, 5
	s_waitcnt vmcnt(7)
	v_mov_b32_e32 v156, v234
	v_mov_b32_e32 v157, v235
	v_lshlrev_b32_e32 v136, 16, v156
	v_and_b32_e32 v137, 0xffff0000, v156
	v_lshlrev_b32_e32 v138, 16, v157
	v_and_b32_e32 v139, 0xffff0000, v157
	v_mul_f32_e32 v23, 0xbfb8aa3b, v136
	v_mul_f32_e32 v27, 0xbfb8aa3b, v137
	v_mul_f32_e32 v29, 0xbfb8aa3b, v138
	v_mul_f32_e32 v45, 0xbfb8aa3b, v139
	v_exp_f32_e32 v23, v23
	v_exp_f32_e32 v27, v27
	v_exp_f32_e32 v29, v29
	v_exp_f32_e32 v45, v45
	v_add_f32_e32 v23, 1.0, v23
	v_add_f32_e32 v27, 1.0, v27
	v_add_f32_e32 v29, 1.0, v29
	v_add_f32_e32 v45, 1.0, v45
	v_rcp_f32_e32 v142, v23
	v_rcp_f32_e32 v143, v27
	v_rcp_f32_e32 v148, v29
	v_rcp_f32_e32 v149, v45
	v_pk_mul_f32 v[132:133], v[132:133], v[136:137]
	v_pk_mul_f32 v[46:47], v[46:47], v[138:139]
	v_pk_mul_f32 v[132:133], v[132:133], v[142:143]
	v_pk_mul_f32 v[46:47], v[46:47], v[148:149]
	v_cvt_pk_bf16_f32 v132, v132, v133
	v_cvt_pk_bf16_f32 v133, v46, v47
	global_store_dwordx2 v[24:25], v[132:133], off offset:1024
	v_lshlrev_b32_e32 v132, 16, v128
	v_and_b32_e32 v133, 0xffff0000, v128
	v_lshlrev_b32_e32 v128, 16, v129
	v_and_b32_e32 v129, 0xffff0000, v129
	v_pk_mul_f32 v[132:133], v[30:31], v[132:133] op_sel:[1,0]
	v_pk_mul_f32 v[128:129], v[30:31], v[128:129] op_sel:[1,0]
	v_pk_fma_f32 v[40:41], v[40:41], v[22:23], v[132:133] op_sel_hi:[1,0,1]
	v_pk_fma_f32 v[42:43], v[42:43], v[22:23], v[128:129] op_sel_hi:[1,0,1]
	v_lshlrev_b32_e32 v136, 16, v130
	v_and_b32_e32 v137, 0xffff0000, v130
	v_lshlrev_b32_e32 v130, 16, v131
	v_and_b32_e32 v131, 0xffff0000, v131
	v_pk_mul_f32 v[40:41], v[26:27], v[40:41] op_sel_hi:[0,1]
	v_pk_mul_f32 v[42:43], v[26:27], v[42:43] op_sel_hi:[0,1]
	v_pk_fma_f32 v[40:41], v[32:33], v[136:137], v[40:41] op_sel_hi:[0,1,1]
	v_pk_fma_f32 v[42:43], v[32:33], v[130:131], v[42:43] op_sel_hi:[0,1,1]
	v_lshlrev_b32_e32 v138, 16, v134
	v_and_b32_e32 v139, 0xffff0000, v134
	v_lshlrev_b32_e32 v134, 16, v135
	v_and_b32_e32 v135, 0xffff0000, v135
	v_pk_mul_f32 v[40:41], v[28:29], v[40:41] op_sel_hi:[0,1]
	v_pk_mul_f32 v[42:43], v[28:29], v[42:43] op_sel_hi:[0,1]
	v_pk_fma_f32 v[40:41], v[34:35], v[138:139], v[40:41] op_sel_hi:[0,1,1]
	v_pk_fma_f32 v[42:43], v[34:35], v[134:135], v[42:43] op_sel_hi:[0,1,1]
	v_pk_mul_f32 v[40:41], v[44:45], v[40:41] op_sel_hi:[0,1]
	v_pk_mul_f32 v[42:43], v[44:45], v[42:43] op_sel_hi:[0,1]
	s_waitcnt vmcnt(7)
	v_mov_b32_e32 v46, v236
	v_mov_b32_e32 v47, v237
	v_lshlrev_b32_e32 v128, 16, v46
	v_and_b32_e32 v129, 0xffff0000, v46
	v_lshlrev_b32_e32 v46, 16, v47
	v_and_b32_e32 v47, 0xffff0000, v47
	v_mul_f32_e32 v23, 0xbfb8aa3b, v128
	v_mul_f32_e32 v27, 0xbfb8aa3b, v129
	v_mul_f32_e32 v29, 0xbfb8aa3b, v46
	v_mul_f32_e32 v45, 0xbfb8aa3b, v47
	v_exp_f32_e32 v23, v23
	v_exp_f32_e32 v27, v27
	v_exp_f32_e32 v29, v29
	v_exp_f32_e32 v45, v45
	v_add_f32_e32 v23, 1.0, v23
	v_add_f32_e32 v27, 1.0, v27
	v_add_f32_e32 v29, 1.0, v29
	v_add_f32_e32 v45, 1.0, v45
	v_rcp_f32_e32 v130, v23
	v_rcp_f32_e32 v131, v27
	v_rcp_f32_e32 v132, v29
	v_rcp_f32_e32 v133, v45
	v_pk_mul_f32 v[40:41], v[40:41], v[128:129]
	v_pk_mul_f32 v[42:43], v[42:43], v[46:47]
	v_pk_mul_f32 v[40:41], v[40:41], v[130:131]
	v_pk_mul_f32 v[42:43], v[42:43], v[132:133]
	v_cvt_pk_bf16_f32 v40, v40, v41
	v_cvt_pk_bf16_f32 v41, v42, v43
	global_store_dwordx2 v[24:25], v[40:41], off offset:1056
	v_lshlrev_b32_e32 v42, 16, v118
	v_and_b32_e32 v43, 0xffff0000, v118
	v_lshlrev_b32_e32 v46, 16, v119
	v_and_b32_e32 v47, 0xffff0000, v119
	v_pk_mul_f32 v[42:43], v[30:31], v[42:43] op_sel:[1,0]
	v_pk_mul_f32 v[46:47], v[30:31], v[46:47] op_sel:[1,0]
	v_pk_fma_f32 v[36:37], v[36:37], v[22:23], v[42:43] op_sel_hi:[1,0,1]
	v_pk_fma_f32 v[38:39], v[38:39], v[22:23], v[46:47] op_sel_hi:[1,0,1]
	v_lshlrev_b32_e32 v118, 16, v124
	v_and_b32_e32 v119, 0xffff0000, v124
	v_lshlrev_b32_e32 v124, 16, v125
	v_and_b32_e32 v125, 0xffff0000, v125
	v_pk_mul_f32 v[36:37], v[26:27], v[36:37] op_sel_hi:[0,1]
	v_pk_mul_f32 v[38:39], v[26:27], v[38:39] op_sel_hi:[0,1]
	v_pk_fma_f32 v[36:37], v[32:33], v[118:119], v[36:37] op_sel_hi:[0,1,1]
	v_pk_fma_f32 v[38:39], v[32:33], v[124:125], v[38:39] op_sel_hi:[0,1,1]
	v_lshlrev_b32_e32 v128, 16, v126
	v_and_b32_e32 v129, 0xffff0000, v126
	v_lshlrev_b32_e32 v126, 16, v127
	v_and_b32_e32 v127, 0xffff0000, v127
	v_pk_mul_f32 v[36:37], v[28:29], v[36:37] op_sel_hi:[0,1]
	v_pk_mul_f32 v[38:39], v[28:29], v[38:39] op_sel_hi:[0,1]
	v_pk_fma_f32 v[36:37], v[34:35], v[128:129], v[36:37] op_sel_hi:[0,1,1]
	v_pk_fma_f32 v[38:39], v[34:35], v[126:127], v[38:39] op_sel_hi:[0,1,1]
	v_pk_mul_f32 v[36:37], v[44:45], v[36:37] op_sel_hi:[0,1]
	v_pk_mul_f32 v[38:39], v[44:45], v[38:39] op_sel_hi:[0,1]
	s_waitcnt vmcnt(7)
	v_mov_b32_e32 v40, v238
	v_mov_b32_e32 v41, v239
	v_lshlrev_b32_e32 v42, 16, v40
	v_and_b32_e32 v43, 0xffff0000, v40
	v_lshlrev_b32_e32 v40, 16, v41
	v_and_b32_e32 v41, 0xffff0000, v41
	v_mul_f32_e32 v23, 0xbfb8aa3b, v42
	v_mul_f32_e32 v27, 0xbfb8aa3b, v43
	v_mul_f32_e32 v29, 0xbfb8aa3b, v40
	v_mul_f32_e32 v45, 0xbfb8aa3b, v41
	v_exp_f32_e32 v23, v23
	v_exp_f32_e32 v27, v27
	v_exp_f32_e32 v29, v29
	v_exp_f32_e32 v45, v45
	v_add_f32_e32 v23, 1.0, v23
	v_add_f32_e32 v27, 1.0, v27
	v_add_f32_e32 v29, 1.0, v29
	v_add_f32_e32 v45, 1.0, v45
	v_rcp_f32_e32 v46, v23
	v_rcp_f32_e32 v47, v27
	v_rcp_f32_e32 v118, v29
	v_rcp_f32_e32 v119, v45
	v_pk_mul_f32 v[36:37], v[36:37], v[42:43]
	v_pk_mul_f32 v[38:39], v[38:39], v[40:41]
	v_pk_mul_f32 v[36:37], v[36:37], v[46:47]
	v_pk_mul_f32 v[38:39], v[38:39], v[118:119]
	v_cvt_pk_bf16_f32 v36, v36, v37
	v_cvt_pk_bf16_f32 v37, v38, v39
	global_store_dwordx2 v[24:25], v[36:37], off offset:1088
	v_lshlrev_b32_e32 v38, 16, v112
	v_and_b32_e32 v39, 0xffff0000, v112
	v_lshlrev_b32_e32 v40, 16, v113
	v_and_b32_e32 v41, 0xffff0000, v113
	v_pk_mul_f32 v[38:39], v[30:31], v[38:39] op_sel:[1,0]
	v_pk_mul_f32 v[40:41], v[30:31], v[40:41] op_sel:[1,0]
	v_pk_fma_f32 v[16:17], v[16:17], v[22:23], v[38:39] op_sel_hi:[1,0,1]
	v_pk_fma_f32 v[18:19], v[18:19], v[22:23], v[40:41] op_sel_hi:[1,0,1]
	v_lshlrev_b32_e32 v42, 16, v110
	v_and_b32_e32 v43, 0xffff0000, v110
	v_lshlrev_b32_e32 v46, 16, v111
	v_and_b32_e32 v47, 0xffff0000, v111
	v_pk_mul_f32 v[16:17], v[26:27], v[16:17] op_sel_hi:[0,1]
	v_pk_mul_f32 v[18:19], v[26:27], v[18:19] op_sel_hi:[0,1]
	v_pk_fma_f32 v[16:17], v[32:33], v[42:43], v[16:17] op_sel_hi:[0,1,1]
	v_pk_fma_f32 v[18:19], v[32:33], v[46:47], v[18:19] op_sel_hi:[0,1,1]
	v_pk_mul_f32 v[16:17], v[28:29], v[16:17] op_sel_hi:[0,1]
	v_pk_mul_f32 v[18:19], v[28:29], v[18:19] op_sel_hi:[0,1]
	v_lshlrev_b32_e32 v110, 16, v116
	v_and_b32_e32 v111, 0xffff0000, v116
	v_lshlrev_b32_e32 v112, 16, v117
	v_and_b32_e32 v113, 0xffff0000, v117
	v_pk_fma_f32 v[16:17], v[34:35], v[110:111], v[16:17] op_sel_hi:[0,1,1]
	v_pk_fma_f32 v[18:19], v[34:35], v[112:113], v[18:19] op_sel_hi:[0,1,1]
	v_pk_mul_f32 v[16:17], v[44:45], v[16:17] op_sel_hi:[0,1]
	v_pk_mul_f32 v[18:19], v[44:45], v[18:19] op_sel_hi:[0,1]
	v_lshl_add_u64 v[116:117], s[70:71], 0, v[20:21]
	v_lshl_add_u64 v[116:117], v[116:117], 0, s[12:13]
	v_lshl_add_u64 v[30:31], v[116:117], 0, v[74:75]
	v_lshlrev_b32_e32 v34, 16, v108
	v_and_b32_e32 v35, 0xffff0000, v108
	s_waitcnt vmcnt(7)
	v_mov_b32_e32 v36, v240
	v_mov_b32_e32 v37, v241
	v_lshlrev_b32_e32 v22, 16, v36
	v_and_b32_e32 v23, 0xffff0000, v36
	v_lshlrev_b32_e32 v26, 16, v37
	v_and_b32_e32 v27, 0xffff0000, v37
	v_mul_f32_e32 v28, 0xbfb8aa3b, v22
	v_mul_f32_e32 v29, 0xbfb8aa3b, v23
	v_mul_f32_e32 v32, 0xbfb8aa3b, v26
	v_mul_f32_e32 v33, 0xbfb8aa3b, v27
	v_exp_f32_e32 v28, v28
	v_exp_f32_e32 v29, v29
	v_exp_f32_e32 v32, v32
	v_exp_f32_e32 v33, v33
	v_add_f32_e32 v28, 1.0, v28
	v_add_f32_e32 v29, 1.0, v29
	v_add_f32_e32 v32, 1.0, v32
	v_add_f32_e32 v33, 1.0, v33
	v_rcp_f32_e32 v28, v28
	v_rcp_f32_e32 v29, v29
	v_rcp_f32_e32 v32, v32
	v_rcp_f32_e32 v33, v33
	v_pk_mul_f32 v[16:17], v[16:17], v[22:23]
	v_pk_mul_f32 v[18:19], v[18:19], v[26:27]
	v_pk_mul_f32 v[16:17], v[16:17], v[28:29]
	v_pk_mul_f32 v[18:19], v[18:19], v[32:33]
	v_cvt_pk_bf16_f32 v16, v16, v17
	v_cvt_pk_bf16_f32 v17, v18, v19
	global_store_dwordx2 v[24:25], v[16:17], off offset:1120
	v_max_f32_e32 v16, v90, v90
	v_max_f32_e32 v17, v69, v69
	v_max_f32_e32 v38, v17, v16
	v_sub_f32_e32 v16, v69, v38
	v_sub_f32_e32 v17, v90, v38
	v_max_f32_e32 v22, v104, v104
	v_exp_f32_e32 v16, v16
	v_exp_f32_e32 v17, v17
	v_max_f32_e32 v23, v102, v102
	v_max_f32_e32 v22, v38, v22
	v_max_f32_e32 v23, v22, v23
	v_mov_b32_e32 v90, v115
	v_sub_f32_e32 v38, v38, v22
	v_sub_f32_e32 v44, v104, v22
	v_sub_f32_e32 v22, v22, v23
	v_sub_f32_e32 v45, v102, v23
	v_exp_f32_e32 v99, v22
	v_lshl_add_u64 v[22:23], s[16:17], 0, v[20:21]
	v_pk_mul_f32 v[20:21], v[90:91], v[16:17]
	v_exp_f32_e32 v95, v38
	v_pk_fma_f32 v[40:41], v[90:91], v[16:17], v[20:21] op_sel_hi:[1,1,0]
	v_lshlrev_b32_e32 v18, 16, v100
	v_exp_f32_e32 v40, v44
	v_and_b32_e32 v19, 0xffff0000, v100
	v_lshlrev_b32_e32 v24, 16, v101
	v_and_b32_e32 v25, 0xffff0000, v101
	v_lshl_add_u64 v[38:39], v[22:23], 0, s[12:13]
	v_pk_mul_f32 v[42:43], v[20:21], v[18:19] op_sel:[1,0]
	v_pk_mul_f32 v[24:25], v[20:21], v[24:25] op_sel:[1,0]
	v_mov_b32_e32 v22, v95
	v_lshl_add_u64 v[18:19], v[38:39], 0, v[74:75]
	v_pk_fma_f32 v[38:39], v[12:13], v[16:17], v[42:43] op_sel_hi:[1,0,1]
	v_pk_fma_f32 v[14:15], v[14:15], v[16:17], v[24:25] op_sel_hi:[1,0,1]
	v_pk_mul_f32 v[24:25], v[22:23], v[38:39] op_sel_hi:[0,1]
	v_pk_mul_f32 v[38:39], v[22:23], v[14:15] op_sel_hi:[0,1]
	v_pk_mul_f32 v[14:15], v[94:95], v[40:41]
	v_lshlrev_b32_e32 v26, 16, v106
	v_pk_fma_f32 v[40:41], v[94:95], v[40:41], v[14:15] op_sel_hi:[1,1,0]
	v_and_b32_e32 v27, 0xffff0000, v106
	v_exp_f32_e32 v40, v45
	v_lshlrev_b32_e32 v32, 16, v107
	v_and_b32_e32 v33, 0xffff0000, v107
	v_mov_b32_e32 v12, v99
	v_pk_fma_f32 v[24:25], v[14:15], v[26:27], v[24:25] op_sel_hi:[0,1,1]
	v_pk_fma_f32 v[32:33], v[14:15], v[32:33], v[38:39] op_sel_hi:[0,1,1]
	v_pk_mul_f32 v[38:39], v[12:13], v[24:25] op_sel_hi:[0,1]
	v_pk_mul_f32 v[24:25], v[98:99], v[40:41]
	v_lshlrev_b32_e32 v36, 16, v109
	v_add_f32_e32 v13, v24, v25
	v_rcp_f32_e32 v26, v13
	v_and_b32_e32 v37, 0xffff0000, v109
	v_pk_mul_f32 v[32:33], v[12:13], v[32:33] op_sel_hi:[0,1]
	v_pk_fma_f32 v[34:35], v[24:25], v[34:35], v[38:39] op_sel_hi:[0,1,1]
	v_pk_fma_f32 v[32:33], v[24:25], v[36:37], v[32:33] op_sel_hi:[0,1,1]
	v_pk_mul_f32 v[34:35], v[26:27], v[34:35] op_sel_hi:[0,1]
	v_pk_mul_f32 v[32:33], v[26:27], v[32:33] op_sel_hi:[0,1]
	v_lshlrev_b32_e32 v42, 16, v97
	v_and_b32_e32 v43, 0xffff0000, v97
	s_waitcnt vmcnt(7)
	v_mov_b32_e32 v28, v242
	v_mov_b32_e32 v29, v243
	v_lshlrev_b32_e32 v36, 16, v28
	v_and_b32_e32 v37, 0xffff0000, v28
	v_lshlrev_b32_e32 v28, 16, v29
	v_and_b32_e32 v29, 0xffff0000, v29
	v_mul_f32_e32 v13, 0xbfb8aa3b, v36
	v_mul_f32_e32 v17, 0xbfb8aa3b, v37
	v_mul_f32_e32 v23, 0xbfb8aa3b, v28
	v_mul_f32_e32 v27, 0xbfb8aa3b, v29
	v_exp_f32_e32 v13, v13
	v_exp_f32_e32 v17, v17
	v_exp_f32_e32 v23, v23
	v_exp_f32_e32 v27, v27
	v_add_f32_e32 v13, 1.0, v13
	v_add_f32_e32 v17, 1.0, v17
	v_add_f32_e32 v23, 1.0, v23
	v_add_f32_e32 v27, 1.0, v27
	v_rcp_f32_e32 v38, v13
	v_rcp_f32_e32 v39, v17
	v_rcp_f32_e32 v40, v23
	v_rcp_f32_e32 v41, v27
	v_pk_mul_f32 v[34:35], v[34:35], v[36:37]
	v_pk_mul_f32 v[28:29], v[32:33], v[28:29]
	v_pk_mul_f32 v[32:33], v[34:35], v[38:39]
	v_pk_mul_f32 v[28:29], v[28:29], v[40:41]
	v_cvt_pk_bf16_f32 v32, v32, v33
	v_cvt_pk_bf16_f32 v33, v28, v29
	global_store_dwordx2 v[18:19], v[32:33], off offset:1024
	v_lshlrev_b32_e32 v32, 16, v88
	v_and_b32_e32 v33, 0xffff0000, v88
	v_lshlrev_b32_e32 v34, 16, v89
	v_and_b32_e32 v35, 0xffff0000, v89
	v_pk_mul_f32 v[32:33], v[20:21], v[32:33] op_sel:[1,0]
	v_pk_mul_f32 v[34:35], v[20:21], v[34:35] op_sel:[1,0]
	v_pk_fma_f32 v[8:9], v[8:9], v[16:17], v[32:33] op_sel_hi:[1,0,1]
	v_pk_fma_f32 v[10:11], v[10:11], v[16:17], v[34:35] op_sel_hi:[1,0,1]
	v_lshlrev_b32_e32 v36, 16, v92
	v_and_b32_e32 v37, 0xffff0000, v92
	v_lshlrev_b32_e32 v38, 16, v93
	v_and_b32_e32 v39, 0xffff0000, v93
	v_pk_mul_f32 v[8:9], v[22:23], v[8:9] op_sel_hi:[0,1]
	v_pk_mul_f32 v[10:11], v[22:23], v[10:11] op_sel_hi:[0,1]
	v_pk_fma_f32 v[8:9], v[14:15], v[36:37], v[8:9] op_sel_hi:[0,1,1]
	v_pk_fma_f32 v[10:11], v[14:15], v[38:39], v[10:11] op_sel_hi:[0,1,1]
	v_lshlrev_b32_e32 v40, 16, v96
	v_and_b32_e32 v41, 0xffff0000, v96
	v_pk_mul_f32 v[8:9], v[12:13], v[8:9] op_sel_hi:[0,1]
	v_pk_mul_f32 v[10:11], v[12:13], v[10:11] op_sel_hi:[0,1]
	v_pk_fma_f32 v[8:9], v[24:25], v[40:41], v[8:9] op_sel_hi:[0,1,1]
	v_pk_fma_f32 v[10:11], v[24:25], v[42:43], v[10:11] op_sel_hi:[0,1,1]
	v_pk_mul_f32 v[8:9], v[26:27], v[8:9] op_sel_hi:[0,1]
	v_pk_mul_f32 v[10:11], v[26:27], v[10:11] op_sel_hi:[0,1]
	v_lshlrev_b32_e32 v38, 16, v87
	v_and_b32_e32 v39, 0xffff0000, v87
	s_waitcnt vmcnt(7)
	v_mov_b32_e32 v28, v244
	v_mov_b32_e32 v29, v245
	v_lshlrev_b32_e32 v32, 16, v28
	v_and_b32_e32 v33, 0xffff0000, v28
	v_lshlrev_b32_e32 v28, 16, v29
	v_and_b32_e32 v29, 0xffff0000, v29
	v_mul_f32_e32 v13, 0xbfb8aa3b, v32
	v_mul_f32_e32 v17, 0xbfb8aa3b, v33
	v_mul_f32_e32 v23, 0xbfb8aa3b, v28
	v_mul_f32_e32 v27, 0xbfb8aa3b, v29
	v_exp_f32_e32 v13, v13
	v_exp_f32_e32 v17, v17
	v_exp_f32_e32 v23, v23
	v_exp_f32_e32 v27, v27
	v_add_f32_e32 v13, 1.0, v13
	v_add_f32_e32 v17, 1.0, v17
	v_add_f32_e32 v23, 1.0, v23
	v_add_f32_e32 v27, 1.0, v27
	v_rcp_f32_e32 v34, v13
	v_rcp_f32_e32 v35, v17
	v_rcp_f32_e32 v36, v23
	v_rcp_f32_e32 v37, v27
	v_pk_mul_f32 v[8:9], v[8:9], v[32:33]
	v_pk_mul_f32 v[10:11], v[10:11], v[28:29]
	v_pk_mul_f32 v[8:9], v[8:9], v[34:35]
	v_pk_mul_f32 v[10:11], v[10:11], v[36:37]
	v_cvt_pk_bf16_f32 v8, v8, v9
	v_cvt_pk_bf16_f32 v9, v10, v11
	global_store_dwordx2 v[18:19], v[8:9], off offset:1056
	v_lshlrev_b32_e32 v10, 16, v82
	v_and_b32_e32 v11, 0xffff0000, v82
	v_lshlrev_b32_e32 v28, 16, v83
	v_and_b32_e32 v29, 0xffff0000, v83
	v_pk_mul_f32 v[10:11], v[20:21], v[10:11] op_sel:[1,0]
	v_pk_mul_f32 v[28:29], v[20:21], v[28:29] op_sel:[1,0]
	v_pk_fma_f32 v[4:5], v[4:5], v[16:17], v[10:11] op_sel_hi:[1,0,1]
	v_pk_fma_f32 v[6:7], v[6:7], v[16:17], v[28:29] op_sel_hi:[1,0,1]
	v_lshlrev_b32_e32 v32, 16, v84
	v_and_b32_e32 v33, 0xffff0000, v84
	v_lshlrev_b32_e32 v34, 16, v85
	v_and_b32_e32 v35, 0xffff0000, v85
	v_pk_mul_f32 v[4:5], v[22:23], v[4:5] op_sel_hi:[0,1]
	v_pk_mul_f32 v[6:7], v[22:23], v[6:7] op_sel_hi:[0,1]
	v_pk_fma_f32 v[4:5], v[14:15], v[32:33], v[4:5] op_sel_hi:[0,1,1]
	v_pk_fma_f32 v[6:7], v[14:15], v[34:35], v[6:7] op_sel_hi:[0,1,1]
	v_lshlrev_b32_e32 v36, 16, v86
	v_and_b32_e32 v37, 0xffff0000, v86
	v_pk_mul_f32 v[4:5], v[12:13], v[4:5] op_sel_hi:[0,1]
	v_pk_mul_f32 v[6:7], v[12:13], v[6:7] op_sel_hi:[0,1]
	v_pk_fma_f32 v[4:5], v[24:25], v[36:37], v[4:5] op_sel_hi:[0,1,1]
	v_pk_fma_f32 v[6:7], v[24:25], v[38:39], v[6:7] op_sel_hi:[0,1,1]
	v_pk_mul_f32 v[4:5], v[26:27], v[4:5] op_sel_hi:[0,1]
	v_pk_mul_f32 v[6:7], v[26:27], v[6:7] op_sel_hi:[0,1]
	s_waitcnt vmcnt(7)
	v_mov_b32_e32 v8, v246
	v_mov_b32_e32 v9, v247
	v_lshlrev_b32_e32 v10, 16, v8
	v_and_b32_e32 v11, 0xffff0000, v8
	v_lshlrev_b32_e32 v8, 16, v9
	v_and_b32_e32 v9, 0xffff0000, v9
	v_mul_f32_e32 v13, 0xbfb8aa3b, v10
	v_mul_f32_e32 v17, 0xbfb8aa3b, v11
	v_mul_f32_e32 v23, 0xbfb8aa3b, v8
	v_mul_f32_e32 v27, 0xbfb8aa3b, v9
	v_exp_f32_e32 v13, v13
	v_exp_f32_e32 v17, v17
	v_exp_f32_e32 v23, v23
	v_exp_f32_e32 v27, v27
	v_add_f32_e32 v13, 1.0, v13
	v_add_f32_e32 v17, 1.0, v17
	v_add_f32_e32 v23, 1.0, v23
	v_add_f32_e32 v27, 1.0, v27
	v_rcp_f32_e32 v28, v13
	v_rcp_f32_e32 v29, v17
	v_rcp_f32_e32 v32, v23
	v_rcp_f32_e32 v33, v27
	v_pk_mul_f32 v[4:5], v[4:5], v[10:11]
	v_pk_mul_f32 v[6:7], v[6:7], v[8:9]
	v_pk_mul_f32 v[4:5], v[4:5], v[28:29]
	v_pk_mul_f32 v[6:7], v[6:7], v[32:33]
	v_cvt_pk_bf16_f32 v4, v4, v5
	v_cvt_pk_bf16_f32 v5, v6, v7
	global_store_dwordx2 v[18:19], v[4:5], off offset:1088
	v_lshlrev_b32_e32 v6, 16, v76
	v_and_b32_e32 v7, 0xffff0000, v76
	v_pk_mul_f32 v[6:7], v[20:21], v[6:7] op_sel:[1,0]
	v_lshlrev_b32_e32 v8, 16, v77
	v_and_b32_e32 v9, 0xffff0000, v77
	v_pk_fma_f32 v[0:1], v[0:1], v[16:17], v[6:7] op_sel_hi:[1,0,1]
	v_lshlrev_b32_e32 v10, 16, v80
	v_and_b32_e32 v11, 0xffff0000, v80
	v_pk_mul_f32 v[8:9], v[20:21], v[8:9] op_sel:[1,0]
	v_pk_mul_f32 v[0:1], v[22:23], v[0:1] op_sel_hi:[0,1]
	v_pk_fma_f32 v[2:3], v[2:3], v[16:17], v[8:9] op_sel_hi:[1,0,1]
	v_pk_fma_f32 v[0:1], v[14:15], v[10:11], v[0:1] op_sel_hi:[0,1,1]
	v_lshlrev_b32_e32 v28, 16, v81
	v_and_b32_e32 v29, 0xffff0000, v81
	v_pk_mul_f32 v[2:3], v[22:23], v[2:3] op_sel_hi:[0,1]
	v_pk_fma_f32 v[2:3], v[14:15], v[28:29], v[2:3] op_sel_hi:[0,1,1]
	v_lshlrev_b32_e32 v30, 16, v78
	v_and_b32_e32 v31, 0xffff0000, v78
	v_lshlrev_b32_e32 v32, 16, v79
	v_and_b32_e32 v33, 0xffff0000, v79
	v_pk_mul_f32 v[0:1], v[12:13], v[0:1] op_sel_hi:[0,1]
	v_pk_mul_f32 v[2:3], v[12:13], v[2:3] op_sel_hi:[0,1]
	v_pk_fma_f32 v[0:1], v[24:25], v[30:31], v[0:1] op_sel_hi:[0,1,1]
	v_pk_fma_f32 v[2:3], v[24:25], v[32:33], v[2:3] op_sel_hi:[0,1,1]
	v_pk_mul_f32 v[0:1], v[26:27], v[0:1] op_sel_hi:[0,1]
	v_pk_mul_f32 v[2:3], v[26:27], v[2:3] op_sel_hi:[0,1]
	s_waitcnt vmcnt(7)
	v_mov_b32_e32 v4, v248
	v_mov_b32_e32 v5, v249
	v_lshlrev_b32_e32 v6, 16, v4
	v_and_b32_e32 v7, 0xffff0000, v4
	v_lshlrev_b32_e32 v4, 16, v5
	v_and_b32_e32 v5, 0xffff0000, v5
	v_mul_f32_e32 v8, 0xbfb8aa3b, v6
	v_mul_f32_e32 v9, 0xbfb8aa3b, v7
	v_mul_f32_e32 v10, 0xbfb8aa3b, v4
	v_mul_f32_e32 v11, 0xbfb8aa3b, v5
	v_exp_f32_e32 v8, v8
	v_exp_f32_e32 v9, v9
	v_exp_f32_e32 v10, v10
	v_exp_f32_e32 v11, v11
	v_add_f32_e32 v8, 1.0, v8
	v_add_f32_e32 v9, 1.0, v9
	v_add_f32_e32 v10, 1.0, v10
	v_add_f32_e32 v11, 1.0, v11
	v_rcp_f32_e32 v8, v8
	v_rcp_f32_e32 v9, v9
	v_rcp_f32_e32 v10, v10
	v_rcp_f32_e32 v11, v11
	v_pk_mul_f32 v[0:1], v[0:1], v[6:7]
	v_pk_mul_f32 v[2:3], v[2:3], v[4:5]
	v_pk_mul_f32 v[0:1], v[0:1], v[8:9]
	v_pk_mul_f32 v[2:3], v[2:3], v[10:11]
	v_cvt_pk_bf16_f32 v0, v0, v1
	v_cvt_pk_bf16_f32 v1, v2, v3
	global_store_dwordx2 v[18:19], v[0:1], off offset:1120
	s_cbranch_scc0 .LBB0_298

.LBB0_342:
	s_waitcnt vmcnt(2)
	v_lshlrev_b32_e32 v66, 16, v17
	v_and_b32_e32 v67, 0xffff0000, v17
	v_add_u32_e32 v88, s88, v39
	v_ashrrev_i32_e32 v17, 12, v39
	v_lshlrev_b32_e32 v68, 16, v18
	v_and_b32_e32 v69, 0xffff0000, v18
	v_cmp_gt_i32_e32 vcc, s5, v88
	v_mul_i32_i24_e32 v18, 0xc00, v17
	s_waitcnt vmcnt(2)
	v_lshlrev_b32_e32 v56, 16, v20
	v_and_b32_e32 v57, 0xffff0000, v20
	v_lshlrev_b32_e32 v64, 16, v16
	v_and_b32_e32 v65, 0xffff0000, v16
	v_lshlrev_b32_e32 v70, 16, v19
	v_and_b32_e32 v71, 0xffff0000, v19
	v_cndmask_b32_e32 v16, v39, v88, vcc
	v_ashrrev_i32_e32 v19, 31, v18
	v_lshlrev_b32_e32 v58, 16, v21
	v_and_b32_e32 v59, 0xffff0000, v21
	v_lshlrev_b32_e32 v60, 16, v22
	v_and_b32_e32 v61, 0xffff0000, v22
	v_lshlrev_b32_e32 v62, 16, v23
	v_and_b32_e32 v63, 0xffff0000, v23
	v_pk_mul_f32 v[22:23], v[56:57], v[56:57]
	v_ashrrev_i32_e32 v17, 31, v16
	v_lshl_add_u64 v[18:19], v[18:19], 2, s[10:11]
	v_pk_mul_f32 v[20:21], v[58:59], v[58:59]
	v_add_f32_e32 v22, v22, v23
	v_lshlrev_b64 v[16:17], 11, v[16:17]
	v_lshl_add_u64 v[48:49], v[18:19], 0, s[12:13]
	v_mov_b32_e32 v31, v25
	v_add_f32_e32 v20, v20, v22
	v_lshl_add_u64 v[16:17], v[26:27], 0, v[16:17]
	v_lshl_add_u64 v[84:85], v[18:19], 0, v[24:25]
	v_lshl_add_u64 v[52:53], v[48:49], 0, v[24:25]
	v_add_f32_e32 v39, v21, v20
	global_load_dwordx4 v[40:43], v[84:85], off offset:16
	global_load_dwordx4 v[44:47], v[84:85], off
	v_lshl_add_u64 v[86:87], v[48:49], 0, v[30:31]
	global_load_dwordx4 v[48:51], v[52:53], off offset:16
	s_nop 0
	global_load_dwordx4 v[52:55], v[52:53], off
	global_load_dwordx4 v[92:95], v[86:87], off
	global_load_dwordx4 v[96:99], v[86:87], off offset:16
	global_load_dwordx4 v[100:103], v[84:85], off offset:2048
	global_load_dwordx4 v[104:107], v[84:85], off offset:2064
	global_load_dwordx4 v[20:23], v[16:17], off nt
	s_nop 0
	global_load_dwordx4 v[16:19], v[16:17], off offset:1024 nt
	v_pk_mul_f32 v[74:75], v[60:61], v[60:61]
	v_pk_mul_f32 v[72:73], v[62:63], v[62:63]
	v_add_f32_e32 v31, v74, v39
	v_add_f32_e32 v31, v75, v31
	v_add_f32_e32 v31, v72, v31
	v_pk_mul_f32 v[82:83], v[64:65], v[64:65]
	v_add_f32_e32 v31, v73, v31
	v_add_f32_e32 v31, v82, v31
	v_pk_mul_f32 v[80:81], v[66:67], v[66:67]
	v_add_f32_e32 v31, v83, v31
	v_add_f32_e32 v31, v80, v31
	v_pk_mul_f32 v[78:79], v[68:69], v[68:69]
	v_add_f32_e32 v31, v81, v31
	v_add_f32_e32 v31, v78, v31
	v_pk_mul_f32 v[76:77], v[70:71], v[70:71]
	v_add_f32_e32 v31, v79, v31
	v_add_f32_e32 v31, v76, v31
	v_add_f32_e32 v31, v77, v31
	ds_bpermute_b32 v39, v32, v31
	s_waitcnt lgkmcnt(0)
	v_add_f32_e32 v31, v31, v39
	ds_bpermute_b32 v39, v33, v31
	s_waitcnt lgkmcnt(0)
	v_add_f32_e32 v31, v31, v39
	ds_bpermute_b32 v39, v34, v31
	s_waitcnt lgkmcnt(0)
	v_add_f32_e32 v31, v31, v39
	ds_bpermute_b32 v39, v35, v31
	s_waitcnt lgkmcnt(0)
	v_add_f32_e32 v31, v31, v39
	ds_bpermute_b32 v39, v36, v31
	s_waitcnt lgkmcnt(0)
	v_add_f32_e32 v31, v31, v39
	ds_bpermute_b32 v39, v37, v31
	s_waitcnt lgkmcnt(0)
	v_add_f32_e32 v31, v31, v39
	v_fmamk_f32 v31, v31, 0x3a800000, v38
	v_mul_f32_e32 v39, 0x4b800000, v31
	v_cmp_gt_f32_e32 vcc, s18, v31
	s_waitcnt vmcnt(2)
	v_pk_add_f32 v[48:49], v[48:49], 1.0 op_sel_hi:[1,0]
	v_cndmask_b32_e32 v31, v31, v39, vcc
	v_rsq_f32_e32 v31, v31
	v_pk_add_f32 v[54:55], v[54:55], 1.0 op_sel_hi:[1,0]
	v_pk_add_f32 v[52:53], v[52:53], 1.0 op_sel_hi:[1,0]
	v_pk_add_f32 v[50:51], v[50:51], 1.0 op_sel_hi:[1,0]
	v_mul_f32_e32 v39, 0x45800000, v31
	v_cndmask_b32_e32 v72, v31, v39, vcc
	v_pk_mul_f32 v[56:57], v[72:73], v[56:57] op_sel_hi:[0,1]
	v_pk_mul_f32 v[58:59], v[72:73], v[58:59] op_sel_hi:[0,1]
	v_pk_mul_f32 v[60:61], v[72:73], v[60:61] op_sel_hi:[0,1]
	v_pk_mul_f32 v[62:63], v[72:73], v[62:63] op_sel_hi:[0,1]
	v_pk_mul_f32 v[56:57], v[4:5], v[56:57]
	v_pk_mul_f32 v[58:59], v[6:7], v[58:59]
	v_pk_mul_f32 v[60:61], v[0:1], v[60:61]
	v_pk_mul_f32 v[62:63], v[2:3], v[62:63]
	v_pk_fma_f32 v[44:45], v[52:53], v[56:57], v[44:45]
	v_pk_fma_f32 v[46:47], v[54:55], v[58:59], v[46:47]
	v_pk_fma_f32 v[48:49], v[48:49], v[60:61], v[40:41]
	v_pk_fma_f32 v[50:51], v[50:51], v[62:63], v[42:43]
	v_cvt_pk_bf16_f32 v40, v44, v45
	v_cvt_pk_bf16_f32 v41, v46, v47
	v_cvt_pk_bf16_f32 v42, v48, v49
	v_cvt_pk_bf16_f32 v43, v50, v51
	global_store_dwordx4 v[28:29], v[40:43], off offset:-1024
	v_pk_mul_f32 v[56:57], v[72:73], v[64:65] op_sel_hi:[0,1]
	v_pk_mul_f32 v[58:59], v[72:73], v[66:67] op_sel_hi:[0,1]
	v_pk_mul_f32 v[60:61], v[72:73], v[68:69] op_sel_hi:[0,1]
	v_pk_mul_f32 v[62:63], v[72:73], v[70:71] op_sel_hi:[0,1]
	v_pk_mul_f32 v[56:57], v[12:13], v[56:57]
	v_pk_mul_f32 v[58:59], v[14:15], v[58:59]
	v_pk_mul_f32 v[60:61], v[8:9], v[60:61]
	v_pk_mul_f32 v[62:63], v[10:11], v[62:63]
	v_cmp_lt_i32_e32 vcc, s4, v88
	v_mov_b32_e32 v39, v88
	s_or_b64 s[16:17], vcc, s[16:17]
	v_pk_add_f32 v[40:41], v[92:93], 1.0 op_sel_hi:[1,0]
	v_pk_add_f32 v[42:43], v[94:95], 1.0 op_sel_hi:[1,0]
	v_pk_add_f32 v[44:45], v[96:97], 1.0 op_sel_hi:[1,0]
	v_pk_add_f32 v[46:47], v[98:99], 1.0 op_sel_hi:[1,0]
	v_pk_fma_f32 v[40:41], v[56:57], v[40:41], v[100:101]
	v_pk_fma_f32 v[42:43], v[58:59], v[42:43], v[102:103]
	v_pk_fma_f32 v[44:45], v[60:61], v[44:45], v[104:105]
	v_pk_fma_f32 v[46:47], v[62:63], v[46:47], v[106:107]
	v_cvt_pk_bf16_f32 v40, v40, v41
	v_cvt_pk_bf16_f32 v41, v42, v43
	v_cvt_pk_bf16_f32 v42, v44, v45
	v_cvt_pk_bf16_f32 v43, v46, v47
	global_store_dwordx4 v[28:29], v[40:43], off
	v_lshl_add_u64 v[28:29], v[28:29], 0, s[14:15]
	s_andn2_b64 exec, exec, s[16:17]
	s_cbranch_execnz .LBB0_342
